# reverse wg order in q-proj GEMM to balance P3; P5+P6 half-grid start offsets
# speedup vs baseline: 1.0075x; 1.0075x over previous
;     __host__ __device__ bool next(int i, Unit& u) const { if (!S.next(i, u)) return false; u.kofs = 128 * u.pn; int n2 = 2; asm volatile("" : "+s"(n2)); u.nt = n2; return true; }
;     __host__ __device__ bool next(int i, Unit& u) const {
;         const long L = (long)i * G + c; if (L >= nwg) return false;
;         map((int)L, u); return true;
; __global__ void __launch_bounds__(512, 2) fwd_megakernel(Args a) {
;     ...
;     {
;     ...
;         { pg8::Gemm g{CQN, WUQ, QL, QL}; pg8::StaticOrder S; S.init(MT, NQ, QL, G, bx); pg8::EpiQ E{QB, ROPE_T}; pg8::gemm_phase<pg8::EpiQ, pg8::StaticOrder>(ldsl, g, S, E); }
.LBB0_355:
	s_or_b64 exec, exec, s[4:5]
	s_waitcnt lgkmcnt(0)
	v_mov_b32_e32 v0, v228
	s_barrier
	s_load_dwordx2 s[14:15], s[92:93], 0xe0
	s_cmp_eq_u32 s94, 0x100
	s_cbranch_scc0 .Lp3rev_a
	s_sub_u32 s73, 0xff, s73
	s_sub_u32 s83, 7, s83
.Lp3rev_a:
	s_cmpk_lt_i32 s73, 0x186
	s_cselect_b64 s[4:5], -1, 0
	v_mov_b32_e32 v8, v228
	s_and_b64 vcc, exec, s[4:5]
	v_readfirstlane_b32 s6, v8
	s_cbranch_vccz .LBB0_357
	s_mul_i32 s1, s83, 48
	s_or_b32 s1, s1, 6
	s_mul_i32 s0, s83, 49
	s_cmp_lt_i32 s83, 6
	s_cselect_b32 s0, s0, s1
	v_readlane_b32 s1, v254, 8
	s_cmp_eq_u32 s94, 0x100
	s_cbranch_scc0 .Lp3rev_b
	s_sub_u32 s1, 31, s1
.Lp3rev_b:
	s_add_i32 s0, s0, s1
	s_mul_hi_i32 s1, s0, 0x2aaaaaab
	s_lshr_b32 s2, s1, 31
	s_ashr_i32 s1, s1, 2
	s_add_i32 s1, s1, s2
	s_lshl_b32 s2, s1, 3
	s_sub_i32 s3, 0x82, s2
	s_min_u32 s3, s3, 8
	s_mul_i32 s1, s1, 24
	s_sub_i32 s7, s0, s1
	v_cvt_f32_ubyte0_e32 v1, s3
	v_cvt_f32_i32_e32 v0, s7
	v_rcp_iflag_f32_e32 v2, v1
	s_ashr_i32 s0, s7, 30
	s_or_b32 s8, s0, 1
	v_mul_f32_e32 v2, v0, v2
	v_trunc_f32_e32 v2, v2
	v_fma_f32 v0, -v2, v1, v0
	v_cvt_i32_f32_e32 v2, v2
	v_cmp_ge_f32_e64 s[0:1], |v0|, v1
	s_and_b64 s[0:1], s[0:1], exec
	s_cselect_b32 s0, s8, 0
	v_readfirstlane_b32 s1, v2
	s_add_i32 s0, s1, s0
	s_sext_i32_i8 s55, s0
	s_mul_i32 s0, s0, s3
	s_sub_i32 s0, s7, s0
	s_sext_i32_i8 s0, s0
	s_add_i32 s56, s2, s0

;     __host__ __device__ bool next(int i, Unit& u) const { if (!S.next(i, u)) return false; u.kofs = 128 * u.pn; int n2 = 2; asm volatile("" : "+s"(n2)); u.nt = n2; return true; }
;     __host__ __device__ bool next(int i, Unit& u) const {
;         const long L = (long)i * G + c; if (L >= nwg) return false;
;         map((int)L, u); return true;
.LBB0_413:
	s_cmp_eq_u32 s94, 0x100
	s_cbranch_scc0 .Lp3rev_c
	s_sub_u32 s73, 0xff, s73
	s_sub_u32 s83, 7, s83

; #define LAS __attribute__((address_space(3)))
; __global__ void __launch_bounds__(512, 2) fwd_megakernel(Args a) {
;     ...
;     PHASE_IDS();
;     {
;         pg8::Gemm g{X1B, WUP, DM, DM}; pg8::StaticOrder S; S.init(MT, FF2, DM, G, bx);
;         pg8::EpiUp E{ACT, HT, UPS, SSQ2, w_ffn_conv, b_ffn_conv, (LAS float*)(ldsl + LDS_HALO)};
;         pg8::gemm_phase<pg8::EpiUp, pg8::StaticOrder>(ldsl, g, S, E);
.LBB0_911:
	s_or_b64 exec, exec, s[4:5]
	s_cmpk_lt_i32 s68, 0xb2c
	s_cselect_b64 s[4:5], -1, 0
	s_waitcnt lgkmcnt(0)
	v_mov_b32_e32 v0, v228
	v_mov_b32_e32 v8, v228
	s_barrier
	v_readlane_b32 vcc_lo, v254, 9
	s_nop 3
	s_cmp_lt_u32 vcc_lo, 128
	s_cbranch_scc1 .Lstag_done_P6
	s_sleep 127
	s_sleep 127
	s_sleep 127
	s_sleep 127
	s_sleep 127
.Lstag_done_P6:
	s_and_b64 vcc, exec, s[4:5]
	v_readfirstlane_b32 s0, v8
	s_cbranch_vccz .LBB0_913
	s_mul_i32 s2, s75, 0x165
	s_add_i32 s2, s2, 4
	s_mul_i32 s1, s75, 0x166
	s_cmp_lt_i32 s75, 4
	s_cselect_b32 s1, s1, s2
	v_readlane_b32 s2, v254, 8
	s_add_i32 s1, s1, s2
	s_mul_hi_i32 s2, s1, 0x2e8ba2e9
	s_lshr_b32 s3, s2, 31
	s_ashr_i32 s2, s2, 5
	s_add_i32 s2, s2, s3
	s_lshl_b32 s6, s2, 3
	s_sub_i32 s3, 0x82, s6
	s_min_u32 s7, s3, 8
	s_mulk_i32 s2, 0xb0
	s_sub_i32 s1, s1, s2
	v_cvt_f32_ubyte0_e32 v1, s7
	v_cvt_f32_i32_e32 v0, s1
	v_rcp_iflag_f32_e32 v2, v1
	s_ashr_i32 s2, s1, 30
	s_or_b32 s8, s2, 1
	v_mul_f32_e32 v2, v0, v2
	v_trunc_f32_e32 v2, v2
	v_fma_f32 v0, -v2, v1, v0
	v_cvt_i32_f32_e32 v2, v2
	v_cmp_ge_f32_e64 s[2:3], |v0|, v1
	s_and_b64 s[2:3], s[2:3], exec
	s_cselect_b32 s2, s8, 0
	v_readfirstlane_b32 s3, v2
	s_add_i32 s2, s3, s2
	s_sext_i32_i16 s14, s2
	s_mul_i32 s2, s2, s7
	s_sub_i32 s1, s1, s2
	s_sext_i32_i16 s1, s1
	s_add_i32 s42, s6, s1
